# prep tile: batch the 7 raw-row staging loads + hoist mu loads (single wait)
# speedup vs baseline: 1.0060x; 1.0060x over previous
; __device__ __forceinline__ void rwkv_prep_tile(const Params& p, int l, int tile, unsigned char* smem) {
;     ...
;   for (int q = tid; q < 34 * 48; q += 256) {
;     const int rr = q / 48, cc = q % 48;
;     const int tr = p0 - 1 + rr;
;     const int col = (cc < 32) ? (256 + cc * 8) : ((cc < 40) ? (768 + d * 64 + (cc - 32) * 8) : (896 + d * 64 + (cc - 40) * 8));
;     uint4 v = make_uint4(0, 0, 0, 0);
;     if (tr >= slo && tr <= shi) v = *(const uint4*)(p.PR + (rowbase + tr) * 1024 + col);
;     *(uint4*)(raw + rr * 384 + cc * 8) = v;
;   }
;   __syncthreads();
;   const float* mu0 = p.rwkv_mu + (size_t)(l * 2 + 0) * 1024;
;   const float* mu1 = p.rwkv_mu + (size_t)(l * 2 + 1) * 1024;
;   {
;     const int ca = tid & 63;
;     const float m0wd = mu0[768 + d * 64 + ca], m1wd = mu1[768 + d * 64 + ca];
;     const float m0ad = mu0[896 + d * 64 + ca], m1ad = mu1[896 + d * 64 + ca];
.LBB0_815:
	v_mov_b32_e32 v72, v189
	s_movk_i32 s42, 0x65f
	s_and_b32 s28, s47, 1
	s_nop 0
	v_cmp_lt_i32_e32 vcc, s42, v72
	s_and_saveexec_b64 s[42:43], vcc
	s_xor_b64 s[42:43], exec, s[42:43]
	s_lshl_b32 s58, s28, 6
	s_or_saveexec_b64 s[56:57], s[42:43]
	s_ashr_i32 s42, s47, 1
	s_mul_hi_i32 s43, s42, 0x78787879
	s_lshr_b32 s44, s43, 31
	s_ashr_i32 s43, s43, 6
	s_add_i32 s43, s43, s44
	s_mulk_i32 s43, 0x88
	s_sub_i32 s42, s42, s43
	s_mul_hi_i32 s43, s47, 0x78787879
	s_lshr_b32 s44, s43, 31
	s_ashr_i32 s43, s43, 7
	s_add_i32 s43, s43, s44
	s_lshl_b32 s62, s42, 5
	s_mul_hi_i32 s45, s43, 0x1100
	s_mul_i32 s44, s43, 0x1100
	v_mov_b32_e32 v1, s58
	s_xor_b64 exec, exec, s[56:57]
	s_cbranch_execz .LBB0_832
	s_cmp_lt_i32 s42, 8
	s_movk_i32 s0, 0x10ff
	s_cselect_b32 s63, 0, 0x100
	s_cselect_b32 s65, 0xff, s0
	s_lshl_b32 s64, s28, 6
	s_add_i32 s66, s62, -1
	v_readlane_b32 s10, v251, 58
	v_readlane_b32 s11, v251, 59
	s_lshl_b32 s67, s28, 7
	s_add_i32 s68, s67, 0x480
	s_addk_i32 s67, 0x400
	s_mov_b32 s1, 0x5555556
	s_movk_i32 s12, 0x660
	v_and_b32_e32 v0, 63, v72
	v_or_b32_e32 v5, s64, v0
	v_lshlrev_b32_e32 v5, 2, v5
	global_load_dword v1, v5, s[52:53] offset:3072
	global_load_dword v2, v5, s[54:55] offset:3072
	global_load_dword v3, v5, s[54:55] offset:3584
	global_load_dword v4, v5, s[52:53] offset:3584
	v_mov_b32_e32 v40, 0x200
	v_mov_b32_e32 v41, s67
	v_mov_b32_e32 v42, s68
	v_mov_b32_e32 v6, v72
	v_mul_hi_u32 v7, v6, s1
	v_mul_u32_u24_e32 v8, 48, v7
	v_sub_u32_e32 v8, v6, v8
	v_add_u32_e32 v9, s66, v7
	v_cmp_le_i32_e32 vcc, s63, v9
	v_cmp_ge_i32_e64 s[2:3], s65, v9
	v_cmp_lt_u32_e64 s[4:5], 31, v8
	v_cmp_lt_u32_e64 s[6:7], 39, v8
	v_add_u32_e32 v9, s44, v9
	v_lshlrev_b32_e32 v9, 11, v9
	v_lshl_add_u32 v9, v8, 4, v9
	v_cndmask_b32_e64 v10, v40, v41, s[4:5]
	v_cndmask_b32_e64 v10, v10, v42, s[6:7]
	v_add_u32_e32 v9, v9, v10
	s_and_b64 s[2:3], vcc, s[2:3]
	v_mov_b32_e32 v80, 0
	v_mov_b32_e32 v81, 0
	v_mov_b32_e32 v82, 0
	v_mov_b32_e32 v83, 0
	s_and_saveexec_b64 s[58:59], s[2:3]
	global_load_dwordx4 v[80:83], v9, s[10:11]
	s_mov_b64 exec, s[58:59]
	v_add_u32_e32 v6, 0x100, v72
	v_mul_hi_u32 v7, v6, s1
	v_mul_u32_u24_e32 v8, 48, v7
	v_sub_u32_e32 v8, v6, v8
	v_add_u32_e32 v9, s66, v7
	v_cmp_le_i32_e32 vcc, s63, v9
	v_cmp_ge_i32_e64 s[2:3], s65, v9
	v_cmp_lt_u32_e64 s[4:5], 31, v8
	v_cmp_lt_u32_e64 s[6:7], 39, v8
	v_add_u32_e32 v9, s44, v9
	v_lshlrev_b32_e32 v9, 11, v9
	v_lshl_add_u32 v9, v8, 4, v9
	v_cndmask_b32_e64 v10, v40, v41, s[4:5]
	v_cndmask_b32_e64 v10, v10, v42, s[6:7]
	v_add_u32_e32 v9, v9, v10
	s_and_b64 s[2:3], vcc, s[2:3]
	v_mov_b32_e32 v84, 0
	v_mov_b32_e32 v85, 0
	v_mov_b32_e32 v86, 0
	v_mov_b32_e32 v87, 0
	s_and_saveexec_b64 s[58:59], s[2:3]
	global_load_dwordx4 v[84:87], v9, s[10:11]
	s_mov_b64 exec, s[58:59]
	v_add_u32_e32 v6, 0x200, v72
	v_mul_hi_u32 v7, v6, s1
	v_mul_u32_u24_e32 v8, 48, v7
	v_sub_u32_e32 v8, v6, v8
	v_add_u32_e32 v9, s66, v7
	v_cmp_le_i32_e32 vcc, s63, v9
	v_cmp_ge_i32_e64 s[2:3], s65, v9
	v_cmp_lt_u32_e64 s[4:5], 31, v8
	v_cmp_lt_u32_e64 s[6:7], 39, v8
	v_add_u32_e32 v9, s44, v9
	v_lshlrev_b32_e32 v9, 11, v9
	v_lshl_add_u32 v9, v8, 4, v9
	v_cndmask_b32_e64 v10, v40, v41, s[4:5]
	v_cndmask_b32_e64 v10, v10, v42, s[6:7]
	v_add_u32_e32 v9, v9, v10
	s_and_b64 s[2:3], vcc, s[2:3]
	v_mov_b32_e32 v88, 0
	v_mov_b32_e32 v89, 0
	v_mov_b32_e32 v90, 0
	v_mov_b32_e32 v91, 0
	s_and_saveexec_b64 s[58:59], s[2:3]
	global_load_dwordx4 v[88:91], v9, s[10:11]
	s_mov_b64 exec, s[58:59]
	v_add_u32_e32 v6, 0x300, v72
	v_mul_hi_u32 v7, v6, s1
	v_mul_u32_u24_e32 v8, 48, v7
	v_sub_u32_e32 v8, v6, v8
	v_add_u32_e32 v9, s66, v7
	v_cmp_le_i32_e32 vcc, s63, v9
	v_cmp_ge_i32_e64 s[2:3], s65, v9
	v_cmp_lt_u32_e64 s[4:5], 31, v8
	v_cmp_lt_u32_e64 s[6:7], 39, v8
	v_add_u32_e32 v9, s44, v9
	v_lshlrev_b32_e32 v9, 11, v9
	v_lshl_add_u32 v9, v8, 4, v9
	v_cndmask_b32_e64 v10, v40, v41, s[4:5]
	v_cndmask_b32_e64 v10, v10, v42, s[6:7]
	v_add_u32_e32 v9, v9, v10
	s_and_b64 s[2:3], vcc, s[2:3]
	v_mov_b32_e32 v92, 0
	v_mov_b32_e32 v93, 0
	v_mov_b32_e32 v94, 0
	v_mov_b32_e32 v95, 0
	s_and_saveexec_b64 s[58:59], s[2:3]
	global_load_dwordx4 v[92:95], v9, s[10:11]
	s_mov_b64 exec, s[58:59]
	v_add_u32_e32 v6, 0x400, v72
	v_mul_hi_u32 v7, v6, s1
	v_mul_u32_u24_e32 v8, 48, v7
	v_sub_u32_e32 v8, v6, v8
	v_add_u32_e32 v9, s66, v7
	v_cmp_le_i32_e32 vcc, s63, v9
	v_cmp_ge_i32_e64 s[2:3], s65, v9
	v_cmp_lt_u32_e64 s[4:5], 31, v8
	v_cmp_lt_u32_e64 s[6:7], 39, v8
	v_add_u32_e32 v9, s44, v9
	v_lshlrev_b32_e32 v9, 11, v9
	v_lshl_add_u32 v9, v8, 4, v9
	v_cndmask_b32_e64 v10, v40, v41, s[4:5]
	v_cndmask_b32_e64 v10, v10, v42, s[6:7]
	v_add_u32_e32 v9, v9, v10
	s_and_b64 s[2:3], vcc, s[2:3]
	v_mov_b32_e32 v96, 0
	v_mov_b32_e32 v97, 0
	v_mov_b32_e32 v98, 0
	v_mov_b32_e32 v99, 0
	s_and_saveexec_b64 s[58:59], s[2:3]
	global_load_dwordx4 v[96:99], v9, s[10:11]
	s_mov_b64 exec, s[58:59]
	v_add_u32_e32 v6, 0x500, v72
	v_mul_hi_u32 v7, v6, s1
	v_mul_u32_u24_e32 v8, 48, v7
	v_sub_u32_e32 v8, v6, v8
	v_add_u32_e32 v9, s66, v7
	v_cmp_le_i32_e32 vcc, s63, v9
	v_cmp_ge_i32_e64 s[2:3], s65, v9
	v_cmp_lt_u32_e64 s[4:5], 31, v8
	v_cmp_lt_u32_e64 s[6:7], 39, v8
	v_add_u32_e32 v9, s44, v9
	v_lshlrev_b32_e32 v9, 11, v9
	v_lshl_add_u32 v9, v8, 4, v9
	v_cndmask_b32_e64 v10, v40, v41, s[4:5]
	v_cndmask_b32_e64 v10, v10, v42, s[6:7]
	v_add_u32_e32 v9, v9, v10
	s_and_b64 s[2:3], vcc, s[2:3]
	v_mov_b32_e32 v100, 0
	v_mov_b32_e32 v101, 0
	v_mov_b32_e32 v102, 0
	v_mov_b32_e32 v103, 0
	s_and_saveexec_b64 s[58:59], s[2:3]
	global_load_dwordx4 v[100:103], v9, s[10:11]
	s_mov_b64 exec, s[58:59]
	v_add_u32_e32 v6, 0x600, v72
	v_mul_hi_u32 v7, v6, s1
	v_mul_u32_u24_e32 v8, 48, v7
	v_sub_u32_e32 v8, v6, v8
	v_add_u32_e32 v9, s66, v7
	v_cmp_le_i32_e32 vcc, s63, v9
	v_cmp_ge_i32_e64 s[2:3], s65, v9
	v_cmp_lt_u32_e64 s[4:5], 31, v8
	v_cmp_lt_u32_e64 s[6:7], 39, v8
	v_add_u32_e32 v9, s44, v9
	v_lshlrev_b32_e32 v9, 11, v9
	v_lshl_add_u32 v9, v8, 4, v9
	v_cndmask_b32_e64 v10, v40, v41, s[4:5]
	v_cndmask_b32_e64 v10, v10, v42, s[6:7]
	v_add_u32_e32 v9, v9, v10
	s_and_b64 s[2:3], vcc, s[2:3]
	v_cmp_gt_u32_e64 s[8:9], s12, v6
	s_and_b64 s[2:3], s[2:3], s[8:9]
	v_mov_b32_e32 v104, 0
	v_mov_b32_e32 v105, 0
	v_mov_b32_e32 v106, 0
	v_mov_b32_e32 v107, 0
	s_and_saveexec_b64 s[58:59], s[2:3]
	global_load_dwordx4 v[104:107], v9, s[10:11]
	s_mov_b64 exec, s[58:59]
	v_lshlrev_b32_e32 v5, 4, v72
	s_waitcnt vmcnt(0)
	ds_write_b128 v5, v[80:83]
	ds_write_b128 v5, v[84:87] offset:4096
	ds_write_b128 v5, v[88:91] offset:8192
	ds_write_b128 v5, v[92:95] offset:12288
	ds_write_b128 v5, v[96:99] offset:16384
	ds_write_b128 v5, v[100:103] offset:20480
	v_cmp_gt_u32_e32 vcc, s12, v6
	s_and_saveexec_b64 s[58:59], vcc
	ds_write_b128 v5, v[104:107] offset:24576
	s_mov_b64 exec, s[58:59]
	s_branch .LBB0_832

; __device__ __forceinline__ float bf2f(bf16_t v) { return __uint_as_float(((unsigned)v) << 16); }
; __device__ __forceinline__ void rwkv_prep_tile(const Params& p, int l, int tile, unsigned char* smem) {
;     ...
;   __syncthreads();
;   const float* mu0 = p.rwkv_mu + (size_t)(l * 2 + 0) * 1024;
;   const float* mu1 = p.rwkv_mu + (size_t)(l * 2 + 1) * 1024;
;   {
;     const int ca = tid & 63;
;     const float m0wd = mu0[768 + d * 64 + ca], m1wd = mu1[768 + d * 64 + ca];
;     const float m0ad = mu0[896 + d * 64 + ca], m1ad = mu1[896 + d * 64 + ca];
; #pragma unroll 2
;     for (int it = 0; it < 8; ++it) {
;       const int i = w + 4 * it;
;       const bf16_t* r0 = raw + (i + 1) * 384 + ca;
;       float u = bf2f(r0[256]), up = bf2f(r0[256 - 384]), un = bf2f(r0[256 + 384]);
.LBB0_832:
	s_or_b64 exec, exec, s[56:57]
	v_and_b32_e32 v0, 63, v72
	s_waitcnt lgkmcnt(0)
	s_barrier
	v_ashrrev_i32_e32 v6, 6, v72
	s_movk_i32 s0, 0x90
	v_mul_lo_u32 v5, v6, s0
	v_lshlrev_b32_e32 v7, 1, v0
	v_mul_lo_u32 v6, v6, s33
	v_readlane_b32 s0, v255, 30
	v_or_b32_e32 v6, v6, v7
	s_add_i32 s42, 0, 0x200
	v_add3_u32 v5, v5, v7, s0
	v_add_u32_e32 v6, s42, v6
	s_mov_b32 s42, 0
